# v11 + FFN-up phases: CUs with 8 of 9 tiles start half a tile late (free slack) to de-synchronise epilogue store bursts
# speedup vs baseline: 1.0116x; 1.0025x over previous
;     __device__ __forceinline__ bool next(int i, Unit& u) const { const int L = i * G + c; if (L >= nunits) return false; const int t = L / S, ks = L % S; u.pm = pm0 + t / nN; u.pn = t % nN; u.ko = ks * Ksub; return true; }
; #define PG8_STAGE(bufoff, gbase, voff) do { _Pragma("unroll") for (int _i = 0; _i < 2; ++_i) \
;         __builtin_amdgcn_global_load_lds((const unsigned*)((const char*)(gbase) + (voff)[_i]), (PG8_LAS unsigned*)(lds + (bufoff) + ldsw + _i * 8192), 16, 0, 0); } while (0)
; #define PG8_WAIT_V(n) asm volatile("s_waitcnt vmcnt(" #n ")" ::: "memory")
; #define PG8_BAR __builtin_amdgcn_s_barrier()
;     __host__ __device__ bool next(int i, Unit& u) const {
;         const long L = (long)i * G + c; if (L >= nwg) return false;
;         int wgid = (int)L; { const int q = nwg / NXCD, r = nwg % NXCD, xcd = wgid % NXCD, off = wgid / NXCD; wgid = (xcd < r ? xcd * (q + 1) : r * (q + 1) + (xcd - r) * q) + off; }
;         const int nig = WGM * nN, gid = wgid / nig, fm = gid * WGM, gsz = (nM - fm) < WGM ? (nM - fm) : WGM;
;         u.pm = fm + ((wgid % nig) % gsz); u.pn = (wgid % nig) / gsz; u.ko = 0; return true;
; template <class Epi, class Sched, bool ALIGN_EPI = false, bool SP2 = false>
; __device__ __forceinline__ void gemm_phase(PG8_LAS unsigned char* lds, const Gemm g, const Sched& S, const Epi& E) {
;     ...
;     const char* cA = (const char*)g.A + (size_t)cur.pm * tstep + (size_t)cur.ko * 2; const char* cB = (const char*)g.Bt + (size_t)cur.pn * tstep + (size_t)cur.ko * 2;
;     S.a_ready(cur);
;     if constexpr (SP2) {
;         PG8_STAGE(PG8_SB(0, 0), cB, voffB); PG8_STAGE(PG8_SB(0, 1), cB + hstep, voffB); PG8_STAGE(PG8_SA(0, 0), cA, voffA); PG8_STAGE(PG8_SA(0, 1), cA + hstep, voffA);
;         if (wr == 1) PG8_BAR;
;         PG8_WAIT_V(2); PG8_BAR;
.LBB0_1009:
	s_cmp_lt_i32 s78, 8
	s_cselect_b64 s[0:1], -1, 0
	s_and_b64 s[0:1], s[0:1], s[4:5]
	s_andn2_b64 vcc, exec, s[0:1]
	s_cbranch_vccnz .LBB0_1026
	s_cmpk_lg_i32 s96, 0x100
	s_cbranch_scc1 .Lstg7_done
	s_cmpk_lt_i32 s74, 0x80
	s_cbranch_scc1 .Lstg7_done
	s_sleep 127
	s_sleep 40
	s_sleep 127
	s_sleep 40
.Lstg7_done:
	s_cmpk_gt_i32 s74, 0x87f
	v_readfirstlane_b32 s5, v198
	s_cbranch_scc1 .LBB0_1026
	v_lshrrev_b32_e32 v1, 5, v198
	v_lshrrev_b32_e32 v3, 1, v198
	v_and_b32_e32 v1, 4, v1
	v_bfe_u32 v2, v198, 2, 2
	s_waitcnt vmcnt(0)
	v_and_b32_e32 v12, 24, v3
	v_add_u32_e32 v10, 0x2000, v233
	v_or3_b32 v1, v1, v2, v12
	v_lshrrev_b32_e32 v2, 7, v10
	s_movk_i32 s3, 0xe0
	v_and_or_b32 v3, v2, s3, v1
	s_movk_i32 s3, 0xf0
	v_bitop3_b32 v11, v233, v235, 48 bitop3:0x6c
	v_and_or_b32 v2, v2, s3, v230
	s_movk_i32 s3, 0x60
	v_or_b32_e32 v4, v11, v205
	v_and_or_b32 v1, v231, s3, v1
	s_movk_i32 s3, 0x70
	v_lshl_or_b32 v134, v1, 11, v4
	v_and_or_b32 v1, v231, s3, v230
	s_lshr_b32 s3, s75, 29
	s_add_i32 s3, s74, s3
	s_lshr_b32 s8, s5, 6
	s_ashr_i32 s4, s3, 3
	s_and_b32 s3, s3, -8
	s_lshr_b32 s10, s5, 8
	s_lshl_b32 s2, s8, 10
	s_sub_i32 s6, s74, s3
	s_cmp_lt_i32 s6, 0
	s_movk_i32 s3, 0x111
	s_cselect_b32 s7, s3, 0x110
	s_mul_i32 s6, s6, s7
	s_add_i32 s4, s6, s4
	s_ashr_i32 s6, s4, 31
	s_lshr_b32 s6, s6, 25
	s_add_i32 s6, s4, s6
	s_ashr_i32 s7, s6, 7
	s_and_b32 s6, s6, 0xffffff80
	s_sub_i32 s6, s4, s6
	s_bfe_i32 s4, s6, 0x80000
	s_bfe_u32 s4, s4, 0x3000c
	s_add_i32 s9, s6, s4
	s_bfe_i32 s4, s9, 0x80000
	s_and_b32 s9, s9, 0xf8
	s_sub_i32 s6, s6, s9
	s_lshl_b32 s7, s7, 3
	s_sext_i32_i16 s4, s4
	s_sext_i32_i8 s6, s6
	s_lshr_b32 s4, s4, 3
	s_add_i32 s20, s7, s6
	s_ashr_i32 s21, s20, 31
	s_bfe_i64 s[12:13], s[4:5], 0x100000
	s_lshl_b64 s[6:7], s[20:21], 19
	s_lshl_b64 s[12:13], s[12:13], 19
	s_add_u32 s24, s65, s12
	s_addc_u32 s25, s66, s13
	s_add_i32 s21, s2, 0x100
	s_add_i32 m0, s21, 0x10000
	v_lshl_or_b32 v130, v3, 11, v4
	global_load_lds_dwordx4 v134, s[24:25]
	s_add_i32 m0, s21, 0x12000
	s_add_u32 s12, s24, 0x40000
	global_load_lds_dwordx4 v130, s[24:25]
	s_addc_u32 s13, s25, 0
	s_add_i32 m0, s21, 0x14000
	v_lshl_or_b32 v136, v1, 11, v4
	global_load_lds_dwordx4 v134, s[12:13]
	s_add_i32 m0, s21, 0x16000
	s_add_u32 s22, s68, s6
	s_addc_u32 s23, s69, s7
	s_add_i32 s28, s21, 0x2000
	global_load_lds_dwordx4 v130, s[12:13]
	s_mov_b32 m0, s21
	s_add_u32 s6, s22, 0x40000
	v_lshl_or_b32 v132, v2, 11, v4
	global_load_lds_dwordx4 v136, s[22:23]
	s_mov_b32 m0, s28
	s_addc_u32 s7, s23, 0
	s_add_i32 s29, s21, 0x4000
	global_load_lds_dwordx4 v132, s[22:23]
	s_mov_b32 m0, s29
	s_add_i32 s30, s21, 0x6000
	global_load_lds_dwordx4 v136, s[6:7]
	s_mov_b32 m0, s30
	v_mov_b32_e32 v135, 0
	global_load_lds_dwordx4 v132, s[6:7]
	v_mov_b32_e32 v131, v135
	v_mov_b32_e32 v137, v135
	v_mov_b32_e32 v133, v135
	s_cmp_eq_u32 s10, 1
	s_mov_b32 s31, 0
	v_lshl_add_u64 v[8:9], s[24:25], 0, v[134:135]
	v_lshl_add_u64 v[4:5], s[24:25], 0, v[130:131]
	v_lshl_add_u64 v[2:3], s[22:23], 0, v[136:137]
	s_cselect_b64 s[6:7], -1, 0
	s_cmp_lg_u32 s10, 1
	v_lshl_add_u64 v[6:7], s[22:23], 0, v[132:133]
	s_cbranch_scc1 .LBB0_1013
	s_barrier

;     __device__ __forceinline__ bool next(int i, Unit& u) const { const int L = i * G + c; if (L >= nunits) return false; const int t = L / S, ks = L % S; u.pm = pm0 + t / nN; u.pn = t % nN; u.ko = ks * Ksub; return true; }
; #define PG8_STAGE(bufoff, gbase, voff) do { _Pragma("unroll") for (int _i = 0; _i < 2; ++_i) \
;         __builtin_amdgcn_global_load_lds((const unsigned*)((const char*)(gbase) + (voff)[_i]), (PG8_LAS unsigned*)(lds + (bufoff) + ldsw + _i * 8192), 16, 0, 0); } while (0)
; #define PG8_WAIT_V(n) asm volatile("s_waitcnt vmcnt(" #n ")" ::: "memory")
; #define PG8_BAR __builtin_amdgcn_s_barrier()
;     __host__ __device__ bool next(int i, Unit& u) const {
;         const long L = (long)i * G + c; if (L >= nwg) return false;
;         int wgid = (int)L; { const int q = nwg / NXCD, r = nwg % NXCD, xcd = wgid % NXCD, off = wgid / NXCD; wgid = (xcd < r ? xcd * (q + 1) : r * (q + 1) + (xcd - r) * q) + off; }
;         const int nig = WGM * nN, gid = wgid / nig, fm = gid * WGM, gsz = (nM - fm) < WGM ? (nM - fm) : WGM;
;         u.pm = fm + ((wgid % nig) % gsz); u.pn = (wgid % nig) / gsz; u.ko = 0; return true;
; template <class Epi, class Sched, bool ALIGN_EPI = false, bool SP2 = false>
; __device__ __forceinline__ void gemm_phase(PG8_LAS unsigned char* lds, const Gemm g, const Sched& S, const Epi& E) {
;     ...
;     const char* cA = (const char*)g.A + (size_t)cur.pm * tstep + (size_t)cur.ko * 2; const char* cB = (const char*)g.Bt + (size_t)cur.pn * tstep + (size_t)cur.ko * 2;
;     S.a_ready(cur);
;     if constexpr (SP2) {
;         PG8_STAGE(PG8_SB(0, 0), cB, voffB); PG8_STAGE(PG8_SB(0, 1), cB + hstep, voffB); PG8_STAGE(PG8_SA(0, 0), cA, voffA); PG8_STAGE(PG8_SA(0, 1), cA + hstep, voffA);
;         if (wr == 1) PG8_BAR;
;         PG8_WAIT_V(2); PG8_BAR;
.LBB0_1614:
	s_cmp_lt_i32 s78, 15
	s_cselect_b64 s[0:1], -1, 0
	s_and_b64 s[0:1], s[0:1], s[4:5]
	s_andn2_b64 vcc, exec, s[0:1]
	s_cbranch_vccnz .LBB0_1631
	s_cmpk_lg_i32 s96, 0x100
	s_cbranch_scc1 .Lstg14_done
	s_cmpk_lt_i32 s74, 0x80
	s_cbranch_scc1 .Lstg14_done
	s_sleep 127
	s_sleep 40
	s_sleep 127
	s_sleep 40
.Lstg14_done:
	v_readlane_b32 s2, v250, 41
	v_readlane_b32 s3, v250, 42
	s_andn2_b64 vcc, exec, s[2:3]
	v_readfirstlane_b32 s5, v198
	s_cbranch_vccnz .LBB0_1631
	v_lshrrev_b32_e32 v0, 5, v198
	v_lshrrev_b32_e32 v2, 1, v198
	v_and_b32_e32 v0, 4, v0
	v_bfe_u32 v1, v198, 2, 2
	s_waitcnt vmcnt(0)
	v_and_b32_e32 v10, 24, v2
	v_add_u32_e32 v8, 0x2000, v233
	v_or3_b32 v0, v0, v1, v10
	v_lshrrev_b32_e32 v1, 7, v8
	s_movk_i32 s4, 0xe0
	v_and_or_b32 v2, v1, s4, v0
	s_movk_i32 s4, 0xf0
	v_bitop3_b32 v9, v233, v235, 48 bitop3:0x6c
	v_and_or_b32 v1, v1, s4, v230
	s_movk_i32 s4, 0x60
	s_add_u32 s2, s76, 0x1a20000
	v_or_b32_e32 v3, v9, v205
	v_and_or_b32 v0, v231, s4, v0
	s_movk_i32 s4, 0x70
	s_addc_u32 s3, s77, 0
	v_lshl_or_b32 v132, v0, 11, v3
	v_and_or_b32 v0, v231, s4, v230
	s_lshr_b32 s4, s75, 29
	s_add_i32 s4, s74, s4
	s_lshr_b32 s8, s5, 6
	s_ashr_i32 s6, s4, 3
	s_and_b32 s4, s4, -8
	s_lshr_b32 s10, s5, 8
	s_lshl_b32 s33, s8, 10
	s_sub_i32 s4, s74, s4
	s_cmp_lt_i32 s4, 0
	s_movk_i32 s38, 0x111
	s_cselect_b32 s7, s38, 0x110
	s_mul_i32 s4, s4, s7
	s_add_i32 s4, s4, s6
	s_ashr_i32 s6, s4, 31
	s_lshr_b32 s6, s6, 25
	s_add_i32 s6, s4, s6
	s_ashr_i32 s7, s6, 7
	s_and_b32 s6, s6, 0xffffff80
	s_sub_i32 s6, s4, s6
	s_bfe_i32 s4, s6, 0x80000
	s_bfe_u32 s4, s4, 0x3000c
	s_add_i32 s9, s6, s4
	s_bfe_i32 s4, s9, 0x80000
	s_and_b32 s9, s9, 0xf8
	s_sub_i32 s6, s6, s9
	s_lshl_b32 s7, s7, 3
	s_sext_i32_i16 s4, s4
	s_sext_i32_i8 s6, s6
	s_lshr_b32 s4, s4, 3
	s_add_i32 s28, s7, s6
	s_ashr_i32 s29, s28, 31
	s_bfe_i64 s[12:13], s[4:5], 0x100000
	s_lshl_b64 s[6:7], s[28:29], 19
	s_lshl_b64 s[12:13], s[12:13], 19
	s_add_u32 s34, s2, s12
	s_addc_u32 s35, s3, s13
	s_add_i32 s29, s33, 0x100
	s_add_i32 m0, s29, 0x10000
	v_lshl_or_b32 v128, v2, 11, v3
	global_load_lds_dwordx4 v132, s[34:35]
	s_add_i32 m0, s29, 0x12000
	s_add_u32 s12, s34, 0x40000
	global_load_lds_dwordx4 v128, s[34:35]
	s_addc_u32 s13, s35, 0
	s_add_i32 m0, s29, 0x14000
	v_lshl_or_b32 v134, v0, 11, v3
	global_load_lds_dwordx4 v132, s[12:13]
	s_add_i32 m0, s29, 0x16000
	s_add_u32 s30, s68, s6
	s_addc_u32 s31, s69, s7
	s_add_i32 s39, s29, 0x2000
	global_load_lds_dwordx4 v128, s[12:13]
	s_mov_b32 m0, s29
	s_add_u32 s6, s30, 0x40000
	v_lshl_or_b32 v130, v1, 11, v3
	global_load_lds_dwordx4 v134, s[30:31]
	s_mov_b32 m0, s39
	s_addc_u32 s7, s31, 0
	s_add_i32 s40, s29, 0x4000
	global_load_lds_dwordx4 v130, s[30:31]
	s_mov_b32 m0, s40
	s_add_i32 s41, s29, 0x6000
	global_load_lds_dwordx4 v134, s[6:7]
	s_mov_b32 m0, s41
	v_mov_b32_e32 v133, 0
	global_load_lds_dwordx4 v130, s[6:7]
	v_mov_b32_e32 v129, v133
	v_mov_b32_e32 v135, v133
	v_mov_b32_e32 v131, v133
	s_cmp_eq_u32 s10, 1
	s_mov_b32 s42, 0
	s_mov_b32 s12, 0x10000
	v_lshl_add_u64 v[6:7], s[34:35], 0, v[132:133]
	v_lshl_add_u64 v[2:3], s[34:35], 0, v[128:129]
	s_mov_b32 s13, 0x14000
	v_lshl_add_u64 v[0:1], s[30:31], 0, v[134:135]
	s_cselect_b64 s[6:7], -1, 0
	s_cmp_lg_u32 s10, 1
	v_lshl_add_u64 v[4:5], s[30:31], 0, v[130:131]
	s_cbranch_scc1 .LBB0_1618
	s_barrier
